# P2a pool mixer (16-row window variant): 12 of the 14 current-row loads issued ahead of the wait for the look-back rows, counted waits adjusted
# baseline (speedup 1.0000x reference)
; #define UNPK8(q, f) const float f[8] = {bf_lo((q).x), bf_hi((q).x), bf_lo((q).y), bf_hi((q).y), bf_lo((q).z), bf_hi((q).z), bf_lo((q).w), bf_hi((q).w)}
; template <int W> __device__ __forceinline__ void pool_run(const bf16_t* up, bf16_t* dp, int t0) {
;     ...
;     for (int i = 0; i < W + 15; ++i) { const int dt = i - (W - 1); const bool ok = (t0 + dt >= 0); const u32x4 v = *(const u32x4*)(up + (ptrdiff_t)(ok ? dt : 0) * PW); q[i] = ok ? v : (u32x4){0u, 0u, 0u, 0u}; }
;     float s[8];
; #pragma unroll
;     for (int e = 0; e < 8; ++e) s[e] = 0.f;
; #pragma unroll
;     for (int i = 0; i < W - 1; ++i) { UNPK8(q[i], f);
; #pragma unroll
;         for (int e = 0; e < 8; ++e) s[e] += f[e]; }
.LBB0_447:
	s_or_b64 exec, exec, s[4:5]
	global_load_dwordx4 v[120:123], v[126:127], off
	global_load_dwordx4 v[104:107], v[126:127], off offset:2048
	v_add_co_u32_e32 v216, vcc, 0x1000, v126
	s_nop 1
	v_addc_co_u32_e32 v217, vcc, 0, v127, vcc
	global_load_dwordx4 v[84:87], v[216:217], off
	global_load_dwordx4 v[64:67], v[216:217], off offset:2048
	v_add_co_u32_e32 v216, vcc, 0x2000, v126
	s_nop 1
	v_addc_co_u32_e32 v217, vcc, 0, v127, vcc
	global_load_dwordx4 v[48:51], v[216:217], off
	global_load_dwordx4 v[40:43], v[216:217], off offset:2048
	v_add_co_u32_e32 v216, vcc, 0x3000, v126
	s_nop 1
	v_addc_co_u32_e32 v217, vcc, 0, v127, vcc
	global_load_dwordx4 v[36:39], v[216:217], off
	global_load_dwordx4 v[32:35], v[216:217], off offset:2048
	v_add_co_u32_e32 v216, vcc, 0x4000, v126
	s_nop 1
	v_addc_co_u32_e32 v217, vcc, 0, v127, vcc
	global_load_dwordx4 v[28:31], v[216:217], off
	global_load_dwordx4 v[24:27], v[216:217], off offset:2048
	v_add_co_u32_e32 v216, vcc, 0x5000, v126
	s_nop 1
	v_addc_co_u32_e32 v217, vcc, 0, v127, vcc
	global_load_dwordx4 v[20:23], v[216:217], off
	global_load_dwordx4 v[16:19], v[216:217], off offset:2048
	v_add_co_u32_e32 v216, vcc, 0x6000, v126
	s_nop 1
	v_addc_co_u32_e32 v217, vcc, 0, v127, vcc
	global_load_dwordx4 v[12:15], v[216:217], off
	global_load_dwordx4 v[8:11], v[216:217], off offset:2048
	v_add_co_u32_e32 v0, vcc, 0x1000, v126
	s_waitcnt vmcnt(14)
	v_lshlrev_b32_e32 v171, 16, v52
	v_addc_co_u32_e32 v1, vcc, 0, v127, vcc
	v_and_b32_e32 v172, 0xffff0000, v52
	v_add_f32_e32 v52, 0, v171
	v_lshlrev_b32_e32 v179, 16, v44
	v_and_b32_e32 v180, 0xffff0000, v44
	v_add_f32_e32 v44, v52, v179
	v_lshlrev_b32_e32 v187, 16, v60
	v_lshlrev_b32_e32 v173, 16, v53
	v_and_b32_e32 v174, 0xffff0000, v53
	v_add_f32_e32 v53, 0, v172
	v_add_f32_e32 v44, v44, v187
	v_lshlrev_b32_e32 v195, 16, v56
	v_lshlrev_b32_e32 v181, 16, v45
	v_and_b32_e32 v182, 0xffff0000, v45
	v_add_f32_e32 v45, v53, v180
	v_and_b32_e32 v188, 0xffff0000, v60
	v_add_f32_e32 v44, v44, v195
	v_lshlrev_b32_e32 v203, 16, v72
	v_lshlrev_b32_e32 v175, 16, v54
	v_and_b32_e32 v176, 0xffff0000, v54
	v_add_f32_e32 v54, 0, v173
	v_add_f32_e32 v45, v45, v188
	v_and_b32_e32 v196, 0xffff0000, v56
	v_add_f32_e32 v44, v44, v203
	v_lshlrev_b32_e32 v163, 16, v68
	v_lshlrev_b32_e32 v177, 16, v55
	v_and_b32_e32 v178, 0xffff0000, v55
	v_add_f32_e32 v55, 0, v174
	v_lshlrev_b32_e32 v183, 16, v46
	v_and_b32_e32 v184, 0xffff0000, v46
	v_add_f32_e32 v46, v54, v181
	v_lshlrev_b32_e32 v189, 16, v61
	v_add_f32_e32 v45, v45, v196
	v_and_b32_e32 v204, 0xffff0000, v72
	v_add_f32_e32 v44, v44, v163
	v_lshlrev_b32_e32 v155, 16, v80
	v_add_f32_e32 v131, 0, v175
	v_add_f32_e32 v132, 0, v176
	v_lshlrev_b32_e32 v185, 16, v47
	v_and_b32_e32 v186, 0xffff0000, v47
	v_add_f32_e32 v47, v55, v182
	v_and_b32_e32 v190, 0xffff0000, v61
	v_add_f32_e32 v46, v46, v189
	v_lshlrev_b32_e32 v197, 16, v57
	v_add_f32_e32 v45, v45, v204
	v_and_b32_e32 v164, 0xffff0000, v68
	v_add_f32_e32 v44, v44, v155
	v_lshlrev_b32_e32 v147, 16, v76
	v_add_f32_e32 v52, v131, v183
	v_add_f32_e32 v53, v132, v184
	v_lshlrev_b32_e32 v191, 16, v62
	v_and_b32_e32 v192, 0xffff0000, v62
	v_add_f32_e32 v47, v47, v190
	v_and_b32_e32 v198, 0xffff0000, v57
	v_add_f32_e32 v46, v46, v197
	v_lshlrev_b32_e32 v205, 16, v73
	v_add_f32_e32 v45, v45, v164
	v_and_b32_e32 v156, 0xffff0000, v80
	v_add_f32_e32 v44, v44, v147
	v_lshlrev_b32_e32 v139, 16, v92
	v_add_f32_e32 v52, v52, v191
	v_add_f32_e32 v53, v53, v192
	v_lshlrev_b32_e32 v199, 16, v58
	v_and_b32_e32 v200, 0xffff0000, v58
	v_add_f32_e32 v47, v47, v198
	v_and_b32_e32 v206, 0xffff0000, v73
	v_add_f32_e32 v46, v46, v205
	v_lshlrev_b32_e32 v165, 16, v69
	v_add_f32_e32 v45, v45, v156
	v_and_b32_e32 v148, 0xffff0000, v76
	v_add_f32_e32 v44, v44, v139
	v_lshlrev_b32_e32 v131, 16, v88
	v_add_f32_e32 v52, v52, v199
	v_add_f32_e32 v53, v53, v200
	v_lshlrev_b32_e32 v207, 16, v74
	v_and_b32_e32 v208, 0xffff0000, v74
	v_add_f32_e32 v47, v47, v206
	v_and_b32_e32 v166, 0xffff0000, v69
	v_add_f32_e32 v46, v46, v165
	v_lshlrev_b32_e32 v157, 16, v81
	v_add_f32_e32 v45, v45, v148
	v_and_b32_e32 v140, 0xffff0000, v92
	v_and_b32_e32 v132, 0xffff0000, v88
	v_add_f32_e32 v44, v44, v131
	v_lshlrev_b32_e32 v88, 16, v100
	v_add_f32_e32 v133, 0, v177
	v_add_f32_e32 v134, 0, v178
	v_add_f32_e32 v52, v52, v207
	v_add_f32_e32 v53, v53, v208
	v_lshlrev_b32_e32 v167, 16, v70
	v_and_b32_e32 v168, 0xffff0000, v70
	v_add_f32_e32 v47, v47, v166
	v_and_b32_e32 v158, 0xffff0000, v81
	v_add_f32_e32 v46, v46, v157
	v_lshlrev_b32_e32 v149, 16, v77
	v_add_f32_e32 v45, v45, v140
	v_add_f32_e32 v44, v44, v88
	v_lshlrev_b32_e32 v76, 16, v96
	v_add_f32_e32 v54, v133, v185
	v_add_f32_e32 v55, v134, v186
	v_lshlrev_b32_e32 v193, 16, v63
	v_and_b32_e32 v194, 0xffff0000, v63
	v_add_f32_e32 v52, v52, v167
	v_add_f32_e32 v53, v53, v168
	v_lshlrev_b32_e32 v159, 16, v82
	v_and_b32_e32 v160, 0xffff0000, v82
	v_add_f32_e32 v47, v47, v158
	v_and_b32_e32 v150, 0xffff0000, v77
	v_add_f32_e32 v46, v46, v149
	v_lshlrev_b32_e32 v141, 16, v93
	v_lshlrev_b32_e32 v133, 16, v89
	v_and_b32_e32 v134, 0xffff0000, v89
	v_add_f32_e32 v45, v45, v132
	v_and_b32_e32 v89, 0xffff0000, v100
	v_add_f32_e32 v44, v44, v76
	v_lshlrev_b32_e32 v68, 16, v112
	v_add_co_u32_e32 v0, vcc, 0x2000, v126
	v_add_f32_e32 v54, v54, v193
	v_add_f32_e32 v55, v55, v194
	v_lshlrev_b32_e32 v201, 16, v59
	v_and_b32_e32 v202, 0xffff0000, v59
	v_add_f32_e32 v52, v52, v159
	v_add_f32_e32 v53, v53, v160
	v_lshlrev_b32_e32 v151, 16, v78
	v_and_b32_e32 v152, 0xffff0000, v78
	v_add_f32_e32 v47, v47, v150
	v_and_b32_e32 v142, 0xffff0000, v93
	v_add_f32_e32 v46, v46, v141
	v_add_f32_e32 v45, v45, v89
	v_and_b32_e32 v77, 0xffff0000, v96
	v_add_f32_e32 v44, v44, v68
	v_lshlrev_b32_e32 v56, 16, v108
	v_addc_co_u32_e32 v1, vcc, 0, v127, vcc
	v_add_f32_e32 v54, v54, v201
	v_add_f32_e32 v55, v55, v202
	v_lshlrev_b32_e32 v209, 16, v75
	v_and_b32_e32 v210, 0xffff0000, v75
	v_add_f32_e32 v52, v52, v151
	v_add_f32_e32 v53, v53, v152
	v_lshlrev_b32_e32 v143, 16, v94
	v_and_b32_e32 v144, 0xffff0000, v94
	v_add_f32_e32 v47, v47, v142
	v_lshlrev_b32_e32 v135, 16, v90
	v_and_b32_e32 v136, 0xffff0000, v90
	v_add_f32_e32 v46, v46, v133
	v_lshlrev_b32_e32 v90, 16, v101
	v_add_f32_e32 v45, v45, v77
	v_and_b32_e32 v69, 0xffff0000, v112
	v_add_f32_e32 v96, v44, v56
	v_lshlrev_b32_e32 v44, 16, v116
	v_add_co_u32_e32 v0, vcc, 0x3000, v126
	v_add_f32_e32 v54, v54, v209
	v_add_f32_e32 v55, v55, v210
	v_lshlrev_b32_e32 v169, 16, v71
	v_and_b32_e32 v170, 0xffff0000, v71
	v_add_f32_e32 v52, v52, v143
	v_add_f32_e32 v53, v53, v144
	v_lshlrev_b32_e32 v137, 16, v91
	v_and_b32_e32 v138, 0xffff0000, v91
	v_add_f32_e32 v47, v47, v134
	v_and_b32_e32 v91, 0xffff0000, v101
	v_add_f32_e32 v46, v46, v90
	v_lshlrev_b32_e32 v78, 16, v97
	v_add_f32_e32 v45, v45, v69
	v_and_b32_e32 v57, 0xffff0000, v108
	v_add_f32_e32 v96, v96, v44
	s_waitcnt vmcnt(13)
; __device__ __forceinline__ unsigned cvt_pk_bf16(float lo, float hi) { unsigned r; asm volatile("v_cvt_pk_bf16_f32 %0, %1, %2" : "=v"(r) : "v"(lo), "v"(hi)); return r; }
; #define UNPK8(q, f) const float f[8] = {bf_lo((q).x), bf_hi((q).x), bf_lo((q).y), bf_hi((q).y), bf_lo((q).z), bf_hi((q).z), bf_lo((q).w), bf_hi((q).w)}
; template <int W> __device__ __forceinline__ void pool_run(const bf16_t* up, bf16_t* dp, int t0) {
;     ...
;     for (int i = 0; i < W - 1; ++i) { UNPK8(q[i], f);
; #pragma unroll
;         for (int e = 0; e < 8; ++e) s[e] += f[e]; }
; #pragma unroll
;     for (int j = 0; j < 16; ++j) {
;         UNPK8(q[j + W - 1], cur);
; #pragma unroll
;         for (int e = 0; e < 8; ++e) s[e] += cur[e];
;         const int cnt = (t0 + j + 1) < W ? (t0 + j + 1) : W; const float inv = 1.0f / (float)cnt;
;         u32x4 o; o.x = cvt_pk_bf16(s[0] * inv - cur[0], s[1] * inv - cur[1]); o.y = cvt_pk_bf16(s[2] * inv - cur[2], s[3] * inv - cur[3]);
;         o.z = cvt_pk_bf16(s[4] * inv - cur[4], s[5] * inv - cur[5]); o.w = cvt_pk_bf16(s[6] * inv - cur[6], s[7] * inv - cur[7]);
;         *(u32x4*)(dp + (size_t)j * PW) = o;
	v_lshlrev_b32_e32 v108, 16, v120
	v_addc_co_u32_e32 v1, vcc, 0, v127, vcc
	v_add_f32_e32 v54, v54, v169
	v_add_f32_e32 v55, v55, v170
	v_lshlrev_b32_e32 v161, 16, v83
	v_and_b32_e32 v162, 0xffff0000, v83
	v_lshlrev_b32_e32 v153, 16, v79
	v_and_b32_e32 v154, 0xffff0000, v79
	v_add_f32_e32 v52, v52, v135
	v_add_f32_e32 v53, v53, v136
	v_lshlrev_b32_e32 v92, 16, v102
	v_and_b32_e32 v93, 0xffff0000, v102
	v_add_f32_e32 v47, v47, v91
	v_and_b32_e32 v79, 0xffff0000, v97
	v_add_f32_e32 v46, v46, v78
	v_lshlrev_b32_e32 v70, 16, v113
	v_add_f32_e32 v97, v45, v57
	v_and_b32_e32 v45, 0xffff0000, v116
	v_add_f32_e32 v116, v96, v108
	v_min_u32_e32 v96, 15, v129
	v_add_co_u32_e32 v0, vcc, 0x4000, v126
	v_add_f32_e32 v54, v54, v161
	v_add_f32_e32 v55, v55, v162
	v_add_f32_e32 v52, v52, v92
	v_add_f32_e32 v53, v53, v93
	v_lshlrev_b32_e32 v80, 16, v98
	v_and_b32_e32 v81, 0xffff0000, v98
	v_add_f32_e32 v47, v47, v79
	v_and_b32_e32 v71, 0xffff0000, v113
	v_add_f32_e32 v46, v46, v70
	v_lshlrev_b32_e32 v58, 16, v109
	v_add_u32_e32 v96, 1, v96
	v_addc_co_u32_e32 v1, vcc, 0, v127, vcc
	v_add_f32_e32 v54, v54, v153
	v_add_f32_e32 v55, v55, v154
	v_lshlrev_b32_e32 v145, 16, v95
	v_and_b32_e32 v146, 0xffff0000, v95
	v_add_f32_e32 v52, v52, v80
	v_add_f32_e32 v53, v53, v81
	v_lshlrev_b32_e32 v72, 16, v114
	v_and_b32_e32 v73, 0xffff0000, v114
	v_add_f32_e32 v47, v47, v71
	v_and_b32_e32 v59, 0xffff0000, v109
	v_add_f32_e32 v98, v46, v58
	v_lshlrev_b32_e32 v46, 16, v117
	v_add_f32_e32 v97, v97, v45
	v_and_b32_e32 v109, 0xffff0000, v120
	v_cvt_f32_ubyte0_e32 v96, v96
	v_add_co_u32_e32 v0, vcc, 0x5000, v126
	v_add_f32_e32 v54, v54, v145
	v_add_f32_e32 v55, v55, v146
	v_lshlrev_b32_e32 v82, 16, v99
	v_and_b32_e32 v83, 0xffff0000, v99
	v_add_f32_e32 v52, v52, v72
	v_add_f32_e32 v53, v53, v73
	v_lshlrev_b32_e32 v60, 16, v110
	v_and_b32_e32 v61, 0xffff0000, v110
	v_add_f32_e32 v99, v47, v59
	v_and_b32_e32 v47, 0xffff0000, v117
	v_add_f32_e32 v98, v98, v46
	v_lshlrev_b32_e32 v110, 16, v121
	v_add_f32_e32 v117, v97, v109
	v_div_scale_f32 v97, s[12:13], v96, v96, 1.0
	v_addc_co_u32_e32 v1, vcc, 0, v127, vcc
	v_add_f32_e32 v54, v54, v137
	v_add_f32_e32 v55, v55, v138
	v_lshlrev_b32_e32 v94, 16, v103
	v_and_b32_e32 v95, 0xffff0000, v103
	v_add_f32_e32 v100, v52, v60
	v_add_f32_e32 v101, v53, v61
	v_lshlrev_b32_e32 v52, 16, v118
	v_and_b32_e32 v53, 0xffff0000, v118
	v_add_f32_e32 v118, v98, v110
	v_rcp_f32_e32 v98, v97
	v_add_co_u32_e32 v0, vcc, 0x6000, v126
	v_add_f32_e32 v54, v54, v94
	v_add_f32_e32 v55, v55, v95
	v_addc_co_u32_e32 v1, vcc, 0, v127, vcc
	v_add_f32_e32 v54, v54, v82
	v_add_f32_e32 v55, v55, v83
	v_lshlrev_b32_e32 v74, 16, v115
	v_and_b32_e32 v75, 0xffff0000, v115
	v_add_co_u32_e32 v0, vcc, 0x7000, v126
	v_add_f32_e32 v54, v54, v74
	v_add_f32_e32 v55, v55, v75
	v_lshlrev_b32_e32 v62, 16, v111
	v_and_b32_e32 v63, 0xffff0000, v111
	v_add_f32_e32 v99, v99, v47
	v_and_b32_e32 v111, 0xffff0000, v121
	v_addc_co_u32_e32 v1, vcc, 0, v127, vcc
	v_add_f32_e32 v102, v54, v62
	v_add_f32_e32 v103, v55, v63
	v_lshlrev_b32_e32 v54, 16, v119
	v_and_b32_e32 v55, 0xffff0000, v119
	v_add_f32_e32 v119, v99, v111
	v_fma_f32 v99, -v97, v98, 1.0
	v_fmac_f32_e32 v98, v99, v98
	v_div_scale_f32 v99, vcc, 1.0, v96, 1.0
	v_mul_f32_e32 v120, v99, v98
	v_fma_f32 v121, -v97, v120, v99
	v_fmac_f32_e32 v120, v121, v98
	v_fma_f32 v97, -v97, v120, v99
	v_div_fmas_f32 v97, v97, v98, v120
	v_div_fixup_f32 v99, v97, v96, 1.0
	v_add_f32_e32 v100, v100, v52
	v_add_f32_e32 v101, v101, v53
	v_lshlrev_b32_e32 v112, 16, v122
	v_and_b32_e32 v113, 0xffff0000, v122
	v_fma_f32 v96, v99, v116, -v108
	v_fma_f32 v97, v99, v117, -v109
	global_load_dwordx4 v[4:7], v[0:1], off
	s_nop 0
	global_load_dwordx4 v[0:3], v[0:1], off offset:2048
	v_add_f32_e32 v102, v102, v54
	v_add_f32_e32 v103, v103, v55
	v_lshlrev_b32_e32 v114, 16, v123
	v_and_b32_e32 v115, 0xffff0000, v123
	v_add_f32_e32 v100, v100, v112
	v_add_f32_e32 v101, v101, v113
	v_cvt_pk_bf16_f32 v96, v96, v97
	v_fma_f32 v97, v99, v118, -v110
	v_fma_f32 v98, v99, v119, -v111
	v_add_f32_e32 v102, v102, v114
	v_add_f32_e32 v103, v103, v115
	v_cvt_pk_bf16_f32 v97, v97, v98
	v_fma_f32 v98, v99, v100, -v112
	v_fma_f32 v108, v99, v101, -v113
	v_cvt_pk_bf16_f32 v98, v98, v108
	v_fma_f32 v108, v99, v102, -v114
	v_fma_f32 v99, v99, v103, -v115
	v_cvt_pk_bf16_f32 v99, v108, v99
	global_store_dwordx4 v[124:125], v[96:99], off sc1
	s_waitcnt vmcnt(15)
	v_lshlrev_b32_e32 v108, 16, v104
	v_and_b32_e32 v104, 0xffff0000, v104
	v_sub_f32_e32 v96, v116, v171
	v_add_f32_e32 v112, v96, v108
	v_min_u32_e32 v96, 14, v129
	v_add_u32_e32 v96, 2, v96
	v_sub_f32_e32 v97, v117, v172
	v_cvt_f32_ubyte0_e32 v96, v96
	v_sub_f32_e32 v98, v118, v173
	v_lshlrev_b32_e32 v109, 16, v105
	v_add_f32_e32 v113, v97, v104
	v_div_scale_f32 v97, s[12:13], v96, v96, 1.0
	v_add_f32_e32 v114, v98, v109
	v_rcp_f32_e32 v98, v97
	v_sub_f32_e32 v99, v119, v174
	v_and_b32_e32 v105, 0xffff0000, v105
	v_add_f32_e32 v115, v99, v105
	v_fma_f32 v99, -v97, v98, 1.0
	v_fmac_f32_e32 v98, v99, v98
	v_div_scale_f32 v99, vcc, 1.0, v96, 1.0
	v_mul_f32_e32 v116, v99, v98
	v_fma_f32 v117, -v97, v116, v99
	v_fmac_f32_e32 v116, v117, v98
	v_fma_f32 v97, -v97, v116, v99
	v_div_fmas_f32 v97, v97, v98, v116
	v_div_fixup_f32 v99, v97, v96, 1.0
	v_sub_f32_e32 v100, v100, v175
	v_sub_f32_e32 v101, v101, v176
	v_lshlrev_b32_e32 v110, 16, v106
	v_and_b32_e32 v106, 0xffff0000, v106
	v_fma_f32 v96, v99, v112, -v108
	v_fma_f32 v97, v99, v113, -v104
	v_sub_f32_e32 v102, v102, v177
	v_sub_f32_e32 v103, v103, v178
	v_lshlrev_b32_e32 v111, 16, v107
	v_and_b32_e32 v107, 0xffff0000, v107
	v_add_f32_e32 v100, v100, v110
	v_add_f32_e32 v101, v101, v106
	v_cvt_pk_bf16_f32 v96, v96, v97
	v_fma_f32 v97, v99, v114, -v109
	v_fma_f32 v98, v99, v115, -v105
	v_add_f32_e32 v102, v102, v111
	v_add_f32_e32 v103, v103, v107
	v_cvt_pk_bf16_f32 v97, v97, v98
	v_fma_f32 v98, v99, v100, -v110
	v_fma_f32 v104, v99, v101, -v106
	v_cvt_pk_bf16_f32 v98, v98, v104
	v_fma_f32 v104, v99, v102, -v111
	v_fma_f32 v99, v99, v103, -v107
	v_cvt_pk_bf16_f32 v99, v104, v99
	global_store_dwordx4 v[124:125], v[96:99], off offset:2048 sc1
	s_waitcnt vmcnt(15)
; __device__ __forceinline__ unsigned cvt_pk_bf16(float lo, float hi) { unsigned r; asm volatile("v_cvt_pk_bf16_f32 %0, %1, %2" : "=v"(r) : "v"(lo), "v"(hi)); return r; }
; #define UNPK8(q, f) const float f[8] = {bf_lo((q).x), bf_hi((q).x), bf_lo((q).y), bf_hi((q).y), bf_lo((q).z), bf_hi((q).z), bf_lo((q).w), bf_hi((q).w)}
; template <int W> __device__ __forceinline__ void pool_run(const bf16_t* up, bf16_t* dp, int t0) {
;     ...
;     for (int j = 0; j < 16; ++j) {
;         UNPK8(q[j + W - 1], cur);
; #pragma unroll
;         for (int e = 0; e < 8; ++e) s[e] += cur[e];
;         const int cnt = (t0 + j + 1) < W ? (t0 + j + 1) : W; const float inv = 1.0f / (float)cnt;
;         u32x4 o; o.x = cvt_pk_bf16(s[0] * inv - cur[0], s[1] * inv - cur[1]); o.y = cvt_pk_bf16(s[2] * inv - cur[2], s[3] * inv - cur[3]);
;         o.z = cvt_pk_bf16(s[4] * inv - cur[4], s[5] * inv - cur[5]); o.w = cvt_pk_bf16(s[6] * inv - cur[6], s[7] * inv - cur[7]);
;         *(u32x4*)(dp + (size_t)j * PW) = o;
;         UNPK8(q[j], old);
; #pragma unroll
;         for (int e = 0; e < 8; ++e) s[e] -= old[e];
;     }
	v_lshlrev_b32_e32 v104, 16, v84
	v_and_b32_e32 v84, 0xffff0000, v84
	v_sub_f32_e32 v96, v112, v179
	v_add_f32_e32 v108, v96, v104
	v_min_u32_e32 v96, 13, v129
	v_add_u32_e32 v96, 3, v96
	v_sub_f32_e32 v97, v113, v180
	v_cvt_f32_ubyte0_e32 v96, v96
	v_sub_f32_e32 v98, v114, v181
	v_lshlrev_b32_e32 v105, 16, v85
	v_add_f32_e32 v109, v97, v84
	v_div_scale_f32 v97, s[12:13], v96, v96, 1.0
	v_add_f32_e32 v110, v98, v105
	v_rcp_f32_e32 v98, v97
	v_sub_f32_e32 v99, v115, v182
	v_and_b32_e32 v85, 0xffff0000, v85
	v_add_f32_e32 v111, v99, v85
	v_fma_f32 v99, -v97, v98, 1.0
	v_fmac_f32_e32 v98, v99, v98
	v_div_scale_f32 v99, vcc, 1.0, v96, 1.0
	v_mul_f32_e32 v112, v99, v98
	v_fma_f32 v113, -v97, v112, v99
	v_fmac_f32_e32 v112, v113, v98
	v_fma_f32 v97, -v97, v112, v99
	v_div_fmas_f32 v97, v97, v98, v112
	v_div_fixup_f32 v96, v97, v96, 1.0
	v_sub_f32_e32 v100, v100, v183
	v_sub_f32_e32 v101, v101, v184
	v_lshlrev_b32_e32 v106, 16, v86
	v_and_b32_e32 v86, 0xffff0000, v86
	v_fma_f32 v97, v96, v108, -v104
	v_fma_f32 v84, v96, v109, -v84
	v_sub_f32_e32 v102, v102, v185
	v_sub_f32_e32 v103, v103, v186
	v_lshlrev_b32_e32 v107, 16, v87
	v_and_b32_e32 v87, 0xffff0000, v87
	v_add_f32_e32 v100, v100, v106
	v_add_f32_e32 v101, v101, v86
	v_cvt_pk_bf16_f32 v84, v97, v84
	v_fma_f32 v97, v96, v110, -v105
	v_fma_f32 v85, v96, v111, -v85
	s_movk_i32 s9, 0x1000
	v_add_f32_e32 v102, v102, v107
	v_add_f32_e32 v103, v103, v87
	v_cvt_pk_bf16_f32 v85, v97, v85
	v_fma_f32 v97, v96, v100, -v106
	v_fma_f32 v86, v96, v101, -v86
	v_cvt_pk_bf16_f32 v86, v97, v86
	v_fma_f32 v97, v96, v102, -v107
	v_fma_f32 v87, v96, v103, -v87
	v_add_co_u32_e32 v96, vcc, s9, v124
	s_movk_i32 s10, 0x2000
	v_cvt_pk_bf16_f32 v87, v97, v87
	s_nop 0
	v_addc_co_u32_e32 v97, vcc, 0, v125, vcc
	v_add_co_u32_e32 v98, vcc, s10, v124
	s_waitcnt vmcnt(14)
	v_lshlrev_b32_e32 v104, 16, v64
	v_addc_co_u32_e32 v99, vcc, 0, v125, vcc
	global_store_dwordx4 v[98:99], v[84:87], off offset:-4096 sc1
	v_and_b32_e32 v64, 0xffff0000, v64
	v_sub_f32_e32 v101, v101, v192
	v_sub_f32_e32 v84, v108, v187
	v_min_u32_e32 v108, 12, v129
	v_add_u32_e32 v108, 4, v108
	v_cvt_f32_ubyte0_e32 v108, v108
	v_sub_f32_e32 v85, v109, v188
	v_div_scale_f32 v109, s[10:11], v108, v108, 1.0
	v_sub_f32_e32 v86, v110, v189
	v_rcp_f32_e32 v110, v109
	v_sub_f32_e32 v87, v111, v190
	v_lshlrev_b32_e32 v105, 16, v65
	v_and_b32_e32 v65, 0xffff0000, v65
	v_fma_f32 v111, -v109, v110, 1.0
	v_fmac_f32_e32 v110, v111, v110
	v_div_scale_f32 v111, vcc, 1.0, v108, 1.0
	v_mul_f32_e32 v112, v111, v110
	v_fma_f32 v113, -v109, v112, v111
	v_fmac_f32_e32 v112, v113, v110
	v_fma_f32 v109, -v109, v112, v111
	v_div_fmas_f32 v109, v109, v110, v112
	v_lshlrev_b32_e32 v106, 16, v66
	v_and_b32_e32 v66, 0xffff0000, v66
	v_add_f32_e32 v84, v84, v104
	v_add_f32_e32 v85, v85, v64
	v_div_fixup_f32 v108, v109, v108, 1.0
	v_sub_f32_e32 v100, v100, v191
	v_sub_f32_e32 v103, v103, v194
	v_lshlrev_b32_e32 v107, 16, v67
	v_and_b32_e32 v67, 0xffff0000, v67
	v_add_f32_e32 v86, v86, v105
	v_add_f32_e32 v87, v87, v65
	v_add_f32_e32 v101, v101, v66
	v_fma_f32 v104, v108, v84, -v104
	v_fma_f32 v64, v108, v85, -v64
	v_sub_f32_e32 v102, v102, v193
	v_add_f32_e32 v100, v100, v106
	v_add_f32_e32 v103, v103, v67
	v_cvt_pk_bf16_f32 v64, v104, v64
	v_fma_f32 v104, v108, v86, -v105
	v_fma_f32 v65, v108, v87, -v65
	v_fma_f32 v66, v108, v101, -v66
	v_add_f32_e32 v102, v102, v107
	v_cvt_pk_bf16_f32 v65, v104, v65
	v_fma_f32 v104, v108, v100, -v106
	v_cvt_pk_bf16_f32 v66, v104, v66
	v_fma_f32 v67, v108, v103, -v67
	v_fma_f32 v104, v108, v102, -v107
	v_cvt_pk_bf16_f32 v67, v104, v67
	global_store_dwordx4 v[96:97], v[64:67], off offset:2048 sc1
	s_waitcnt vmcnt(15)
	v_lshlrev_b32_e32 v96, 16, v48
	v_and_b32_e32 v48, 0xffff0000, v48
	v_sub_f32_e32 v66, v86, v197
	v_sub_f32_e32 v86, v102, v201
	v_min_u32_e32 v102, 11, v129
	v_add_u32_e32 v102, 5, v102
	v_cvt_f32_ubyte0_e32 v102, v102
	v_sub_f32_e32 v67, v87, v198
	v_sub_f32_e32 v87, v103, v202
	v_div_scale_f32 v103, s[10:11], v102, v102, 1.0
	v_rcp_f32_e32 v104, v103
	v_sub_f32_e32 v64, v84, v195
	v_sub_f32_e32 v65, v85, v196
	v_lshlrev_b32_e32 v97, 16, v49
	v_fma_f32 v105, -v103, v104, 1.0
	v_fmac_f32_e32 v104, v105, v104
	v_div_scale_f32 v105, vcc, 1.0, v102, 1.0
	v_mul_f32_e32 v106, v105, v104
	v_fma_f32 v107, -v103, v106, v105
	v_fmac_f32_e32 v106, v107, v104
	v_fma_f32 v103, -v103, v106, v105
	v_div_fmas_f32 v103, v103, v104, v106
	v_and_b32_e32 v49, 0xffff0000, v49
	v_add_f32_e32 v64, v64, v96
	v_add_f32_e32 v65, v65, v48
	v_div_fixup_f32 v102, v103, v102, 1.0
	v_sub_f32_e32 v84, v100, v199
	v_sub_f32_e32 v85, v101, v200
	v_lshlrev_b32_e32 v100, 16, v50
	v_and_b32_e32 v50, 0xffff0000, v50
	v_add_f32_e32 v66, v66, v97
	v_add_f32_e32 v67, v67, v49
	v_fma_f32 v96, v102, v64, -v96
	v_fma_f32 v48, v102, v65, -v48
	v_lshlrev_b32_e32 v101, 16, v51
	v_and_b32_e32 v51, 0xffff0000, v51
	v_add_f32_e32 v84, v84, v100
	v_add_f32_e32 v85, v85, v50
	v_cvt_pk_bf16_f32 v48, v96, v48
	v_fma_f32 v96, v102, v66, -v97
	v_fma_f32 v49, v102, v67, -v49
	v_add_f32_e32 v86, v86, v101
	v_add_f32_e32 v87, v87, v51
	v_cvt_pk_bf16_f32 v49, v96, v49
	v_fma_f32 v96, v102, v84, -v100
	v_fma_f32 v50, v102, v85, -v50
	v_cvt_pk_bf16_f32 v50, v96, v50
	v_fma_f32 v96, v102, v86, -v101
	v_fma_f32 v51, v102, v87, -v51
	v_cvt_pk_bf16_f32 v51, v96, v51
	v_min_u32_e32 v96, 10, v129
	v_add_u32_e32 v96, 6, v96
	v_cvt_f32_ubyte0_e32 v96, v96
	v_div_scale_f32 v97, s[10:11], v96, v96, 1.0
	v_rcp_f32_e32 v100, v97
	global_store_dwordx4 v[98:99], v[48:51], off sc1
	s_movk_i32 s7, 0x3000
	s_movk_i32 s8, 0x4000
	v_fma_f32 v101, -v97, v100, 1.0
	v_fmac_f32_e32 v100, v101, v100
	v_div_scale_f32 v101, vcc, 1.0, v96, 1.0
	v_mul_f32_e32 v102, v101, v100
	v_fma_f32 v103, -v97, v102, v101
	v_fmac_f32_e32 v102, v103, v100
	v_fma_f32 v97, -v97, v102, v101
	v_sub_f32_e32 v48, v64, v203
	v_sub_f32_e32 v49, v65, v204
	v_sub_f32_e32 v64, v84, v207
	s_waitcnt vmcnt(15)
; __device__ __forceinline__ unsigned cvt_pk_bf16(float lo, float hi) { unsigned r; asm volatile("v_cvt_pk_bf16_f32 %0, %1, %2" : "=v"(r) : "v"(lo), "v"(hi)); return r; }
; #define UNPK8(q, f) const float f[8] = {bf_lo((q).x), bf_hi((q).x), bf_lo((q).y), bf_hi((q).y), bf_lo((q).z), bf_hi((q).z), bf_lo((q).w), bf_hi((q).w)}
; template <int W> __device__ __forceinline__ void pool_run(const bf16_t* up, bf16_t* dp, int t0) {
;     ...
;     for (int j = 0; j < 16; ++j) {
;         UNPK8(q[j + W - 1], cur);
; #pragma unroll
;         for (int e = 0; e < 8; ++e) s[e] += cur[e];
;         const int cnt = (t0 + j + 1) < W ? (t0 + j + 1) : W; const float inv = 1.0f / (float)cnt;
;         u32x4 o; o.x = cvt_pk_bf16(s[0] * inv - cur[0], s[1] * inv - cur[1]); o.y = cvt_pk_bf16(s[2] * inv - cur[2], s[3] * inv - cur[3]);
;         o.z = cvt_pk_bf16(s[4] * inv - cur[4], s[5] * inv - cur[5]); o.w = cvt_pk_bf16(s[6] * inv - cur[6], s[7] * inv - cur[7]);
;         *(u32x4*)(dp + (size_t)j * PW) = o;
;         UNPK8(q[j], old);
; #pragma unroll
;         for (int e = 0; e < 8; ++e) s[e] -= old[e];
;     }
	v_lshlrev_b32_e32 v84, 16, v40
	v_and_b32_e32 v40, 0xffff0000, v40
	v_div_fmas_f32 v97, v97, v100, v102
	v_sub_f32_e32 v50, v66, v205
	v_sub_f32_e32 v51, v67, v206
	v_sub_f32_e32 v65, v85, v208
	v_lshlrev_b32_e32 v85, 16, v41
	v_and_b32_e32 v41, 0xffff0000, v41
	v_add_f32_e32 v48, v48, v84
	v_add_f32_e32 v49, v49, v40
	v_div_fixup_f32 v96, v97, v96, 1.0
	v_sub_f32_e32 v66, v86, v209
	v_sub_f32_e32 v67, v87, v210
	v_lshlrev_b32_e32 v86, 16, v42
	v_and_b32_e32 v42, 0xffff0000, v42
	v_lshlrev_b32_e32 v87, 16, v43
	v_and_b32_e32 v43, 0xffff0000, v43
	v_add_f32_e32 v50, v50, v85
	v_add_f32_e32 v51, v51, v41
	v_fma_f32 v84, v96, v48, -v84
	v_fma_f32 v40, v96, v49, -v40
	v_add_f32_e32 v64, v64, v86
	v_add_f32_e32 v65, v65, v42
	v_add_f32_e32 v67, v67, v43
	v_cvt_pk_bf16_f32 v40, v84, v40
	v_fma_f32 v84, v96, v50, -v85
	v_fma_f32 v41, v96, v51, -v41
	v_add_f32_e32 v66, v66, v87
	v_cvt_pk_bf16_f32 v41, v84, v41
	v_fma_f32 v84, v96, v64, -v86
	v_fma_f32 v42, v96, v65, -v42
	v_fma_f32 v43, v96, v67, -v43
	v_cvt_pk_bf16_f32 v42, v84, v42
	v_fma_f32 v84, v96, v66, -v87
	v_cvt_pk_bf16_f32 v43, v84, v43
	global_store_dwordx4 v[98:99], v[40:43], off offset:2048 sc1
	s_movk_i32 s5, 0x5000
	s_movk_i32 s6, 0x6000
	v_sub_f32_e32 v40, v48, v163
	v_sub_f32_e32 v48, v64, v167
	s_waitcnt vmcnt(15)
	v_lshlrev_b32_e32 v64, 16, v36
	v_add_f32_e32 v84, v40, v64
	v_min_u32_e32 v40, 9, v129
	v_add_u32_e32 v40, 7, v40
	v_sub_f32_e32 v41, v49, v164
	v_and_b32_e32 v36, 0xffff0000, v36
	v_cvt_f32_ubyte0_e32 v40, v40
	v_sub_f32_e32 v42, v50, v165
	v_sub_f32_e32 v49, v65, v168
	v_lshlrev_b32_e32 v65, 16, v37
	v_add_f32_e32 v85, v41, v36
	v_div_scale_f32 v41, s[10:11], v40, v40, 1.0
	v_add_f32_e32 v86, v42, v65
	v_rcp_f32_e32 v42, v41
	v_sub_f32_e32 v43, v51, v166
	v_and_b32_e32 v37, 0xffff0000, v37
	v_add_f32_e32 v87, v43, v37
	v_fma_f32 v43, -v41, v42, 1.0
	v_fmac_f32_e32 v42, v43, v42
	v_div_scale_f32 v43, vcc, 1.0, v40, 1.0
	v_mul_f32_e32 v96, v43, v42
	v_fma_f32 v97, -v41, v96, v43
	v_fmac_f32_e32 v96, v97, v42
	v_fma_f32 v41, -v41, v96, v43
	v_div_fmas_f32 v41, v41, v42, v96
	v_div_fixup_f32 v40, v41, v40, 1.0
	v_sub_f32_e32 v50, v66, v169
	v_lshlrev_b32_e32 v66, 16, v38
	v_and_b32_e32 v38, 0xffff0000, v38
	v_fma_f32 v41, v40, v84, -v64
	v_fma_f32 v36, v40, v85, -v36
	v_sub_f32_e32 v51, v67, v170
	v_lshlrev_b32_e32 v67, 16, v39
	v_and_b32_e32 v39, 0xffff0000, v39
	v_add_f32_e32 v48, v48, v66
	v_add_f32_e32 v49, v49, v38
	v_cvt_pk_bf16_f32 v36, v41, v36
	v_fma_f32 v41, v40, v86, -v65
	v_fma_f32 v37, v40, v87, -v37
	v_add_f32_e32 v50, v50, v67
	v_add_f32_e32 v51, v51, v39
	v_cvt_pk_bf16_f32 v37, v41, v37
	v_fma_f32 v41, v40, v48, -v66
	v_fma_f32 v38, v40, v49, -v38
	v_cvt_pk_bf16_f32 v38, v41, v38
	v_fma_f32 v41, v40, v50, -v67
	v_fma_f32 v39, v40, v51, -v39
	v_add_co_u32_e32 v40, vcc, s7, v124
	v_cvt_pk_bf16_f32 v39, v41, v39
	s_waitcnt vmcnt(14)
	v_lshlrev_b32_e32 v64, 16, v32
	v_addc_co_u32_e32 v41, vcc, 0, v125, vcc
	v_add_co_u32_e32 v42, vcc, s8, v124
	v_and_b32_e32 v32, 0xffff0000, v32
	s_nop 0
	v_addc_co_u32_e32 v43, vcc, 0, v125, vcc
	global_store_dwordx4 v[42:43], v[36:39], off offset:-4096 sc1
	v_sub_f32_e32 v49, v49, v160
	v_lshlrev_b32_e32 v65, 16, v33
	v_sub_f32_e32 v36, v84, v155
	v_min_u32_e32 v84, 8, v129
	v_add_u32_e32 v84, 8, v84
	v_cvt_f32_ubyte0_e32 v84, v84
	v_sub_f32_e32 v37, v85, v156
	v_div_scale_f32 v85, s[8:9], v84, v84, 1.0
	v_sub_f32_e32 v38, v86, v157
	v_rcp_f32_e32 v86, v85
	v_sub_f32_e32 v39, v87, v158
	v_and_b32_e32 v33, 0xffff0000, v33
	v_lshlrev_b32_e32 v66, 16, v34
	v_fma_f32 v87, -v85, v86, 1.0
	v_fmac_f32_e32 v86, v87, v86
	v_div_scale_f32 v87, vcc, 1.0, v84, 1.0
	v_mul_f32_e32 v96, v87, v86
	v_fma_f32 v97, -v85, v96, v87
	v_fmac_f32_e32 v96, v97, v86
	v_fma_f32 v85, -v85, v96, v87
	v_div_fmas_f32 v85, v85, v86, v96
	v_and_b32_e32 v34, 0xffff0000, v34
	v_add_f32_e32 v36, v36, v64
	v_add_f32_e32 v37, v37, v32
	v_div_fixup_f32 v84, v85, v84, 1.0
	v_sub_f32_e32 v48, v48, v159
	v_sub_f32_e32 v51, v51, v162
	v_lshlrev_b32_e32 v67, 16, v35
	v_and_b32_e32 v35, 0xffff0000, v35
	v_add_f32_e32 v38, v38, v65
	v_add_f32_e32 v39, v39, v33
	v_add_f32_e32 v49, v49, v34
	v_fma_f32 v64, v84, v36, -v64
	v_fma_f32 v32, v84, v37, -v32
	v_sub_f32_e32 v50, v50, v161
	v_add_f32_e32 v48, v48, v66
	v_add_f32_e32 v51, v51, v35
	v_cvt_pk_bf16_f32 v32, v64, v32
	v_fma_f32 v64, v84, v38, -v65
	v_fma_f32 v33, v84, v39, -v33
	v_fma_f32 v34, v84, v49, -v34
	v_add_f32_e32 v50, v50, v67
	v_cvt_pk_bf16_f32 v33, v64, v33
	v_fma_f32 v64, v84, v48, -v66
	v_cvt_pk_bf16_f32 v34, v64, v34
	v_fma_f32 v35, v84, v51, -v35
	v_fma_f32 v64, v84, v50, -v67
	v_cvt_pk_bf16_f32 v35, v64, v35
	global_store_dwordx4 v[40:41], v[32:35], off offset:2048 sc1
	s_waitcnt vmcnt(15)
; __device__ __forceinline__ unsigned cvt_pk_bf16(float lo, float hi) { unsigned r; asm volatile("v_cvt_pk_bf16_f32 %0, %1, %2" : "=v"(r) : "v"(lo), "v"(hi)); return r; }
; #define UNPK8(q, f) const float f[8] = {bf_lo((q).x), bf_hi((q).x), bf_lo((q).y), bf_hi((q).y), bf_lo((q).z), bf_hi((q).z), bf_lo((q).w), bf_hi((q).w)}
; template <int W> __device__ __forceinline__ void pool_run(const bf16_t* up, bf16_t* dp, int t0) {
;     ...
;     for (int j = 0; j < 16; ++j) {
;         UNPK8(q[j + W - 1], cur);
; #pragma unroll
;         for (int e = 0; e < 8; ++e) s[e] += cur[e];
;         const int cnt = (t0 + j + 1) < W ? (t0 + j + 1) : W; const float inv = 1.0f / (float)cnt;
;         u32x4 o; o.x = cvt_pk_bf16(s[0] * inv - cur[0], s[1] * inv - cur[1]); o.y = cvt_pk_bf16(s[2] * inv - cur[2], s[3] * inv - cur[3]);
;         o.z = cvt_pk_bf16(s[4] * inv - cur[4], s[5] * inv - cur[5]); o.w = cvt_pk_bf16(s[6] * inv - cur[6], s[7] * inv - cur[7]);
;         *(u32x4*)(dp + (size_t)j * PW) = o;
;         UNPK8(q[j], old);
; #pragma unroll
;         for (int e = 0; e < 8; ++e) s[e] -= old[e];
;     }
	v_lshlrev_b32_e32 v40, 16, v28
	v_and_b32_e32 v28, 0xffff0000, v28
	v_sub_f32_e32 v34, v38, v149
	v_sub_f32_e32 v38, v50, v153
	v_min_u32_e32 v50, 7, v129
	v_add_u32_e32 v50, 9, v50
	v_cvt_f32_ubyte0_e32 v50, v50
	v_sub_f32_e32 v35, v39, v150
	v_sub_f32_e32 v39, v51, v154
	v_div_scale_f32 v51, s[8:9], v50, v50, 1.0
	v_rcp_f32_e32 v64, v51
	v_sub_f32_e32 v32, v36, v147
	v_sub_f32_e32 v33, v37, v148
	v_lshlrev_b32_e32 v41, 16, v29
	v_fma_f32 v65, -v51, v64, 1.0
	v_fmac_f32_e32 v64, v65, v64
	v_div_scale_f32 v65, vcc, 1.0, v50, 1.0
	v_mul_f32_e32 v66, v65, v64
	v_fma_f32 v67, -v51, v66, v65
	v_fmac_f32_e32 v66, v67, v64
	v_fma_f32 v51, -v51, v66, v65
	v_div_fmas_f32 v51, v51, v64, v66
	v_and_b32_e32 v29, 0xffff0000, v29
	v_add_f32_e32 v32, v32, v40
	v_add_f32_e32 v33, v33, v28
	v_div_fixup_f32 v50, v51, v50, 1.0
	v_sub_f32_e32 v36, v48, v151
	v_sub_f32_e32 v37, v49, v152
	v_lshlrev_b32_e32 v48, 16, v30
	v_and_b32_e32 v30, 0xffff0000, v30
	v_add_f32_e32 v34, v34, v41
	v_add_f32_e32 v35, v35, v29
	v_fma_f32 v40, v50, v32, -v40
	v_fma_f32 v28, v50, v33, -v28
	v_lshlrev_b32_e32 v49, 16, v31
	v_and_b32_e32 v31, 0xffff0000, v31
	v_add_f32_e32 v36, v36, v48
	v_add_f32_e32 v37, v37, v30
	v_cvt_pk_bf16_f32 v28, v40, v28
	v_fma_f32 v40, v50, v34, -v41
	v_fma_f32 v29, v50, v35, -v29
	v_add_f32_e32 v38, v38, v49
	v_add_f32_e32 v39, v39, v31
	v_cvt_pk_bf16_f32 v29, v40, v29
	v_fma_f32 v40, v50, v36, -v48
	v_fma_f32 v30, v50, v37, -v30
	v_cvt_pk_bf16_f32 v30, v40, v30
	v_fma_f32 v40, v50, v38, -v49
	v_fma_f32 v31, v50, v39, -v31
	v_cvt_pk_bf16_f32 v31, v40, v31
	v_min_u32_e32 v40, 6, v129
	v_add_u32_e32 v40, 10, v40
	v_cvt_f32_ubyte0_e32 v40, v40
	v_div_scale_f32 v41, s[8:9], v40, v40, 1.0
	v_rcp_f32_e32 v48, v41
	global_store_dwordx4 v[42:43], v[28:31], off sc1
	s_movk_i32 s4, 0x7000
	v_fma_f32 v49, -v41, v48, 1.0
	v_fmac_f32_e32 v48, v49, v48
	v_div_scale_f32 v49, vcc, 1.0, v40, 1.0
	v_mul_f32_e32 v50, v49, v48
	v_fma_f32 v51, -v41, v50, v49
	v_fmac_f32_e32 v50, v51, v48
	v_fma_f32 v41, -v41, v50, v49
	v_sub_f32_e32 v28, v32, v139
	v_sub_f32_e32 v29, v33, v140
	v_sub_f32_e32 v32, v36, v143
	s_waitcnt vmcnt(15)
	v_lshlrev_b32_e32 v36, 16, v24
	v_and_b32_e32 v24, 0xffff0000, v24
	v_div_fmas_f32 v41, v41, v48, v50
	v_sub_f32_e32 v30, v34, v141
	v_sub_f32_e32 v31, v35, v142
	v_sub_f32_e32 v33, v37, v144
	v_lshlrev_b32_e32 v37, 16, v25
	v_and_b32_e32 v25, 0xffff0000, v25
	v_add_f32_e32 v28, v28, v36
	v_add_f32_e32 v29, v29, v24
	v_div_fixup_f32 v40, v41, v40, 1.0
	v_sub_f32_e32 v34, v38, v145
	v_sub_f32_e32 v35, v39, v146
	v_lshlrev_b32_e32 v38, 16, v26
	v_and_b32_e32 v26, 0xffff0000, v26
	v_lshlrev_b32_e32 v39, 16, v27
	v_and_b32_e32 v27, 0xffff0000, v27
	v_add_f32_e32 v30, v30, v37
	v_add_f32_e32 v31, v31, v25
	v_fma_f32 v36, v40, v28, -v36
	v_fma_f32 v24, v40, v29, -v24
	v_add_f32_e32 v32, v32, v38
	v_add_f32_e32 v33, v33, v26
	v_add_f32_e32 v35, v35, v27
	v_cvt_pk_bf16_f32 v24, v36, v24
	v_fma_f32 v36, v40, v30, -v37
	v_fma_f32 v25, v40, v31, -v25
	v_add_f32_e32 v34, v34, v39
	v_cvt_pk_bf16_f32 v25, v36, v25
	v_fma_f32 v36, v40, v32, -v38
	v_fma_f32 v26, v40, v33, -v26
	v_fma_f32 v27, v40, v35, -v27
	v_cvt_pk_bf16_f32 v26, v36, v26
	v_fma_f32 v36, v40, v34, -v39
	v_cvt_pk_bf16_f32 v27, v36, v27
	global_store_dwordx4 v[42:43], v[24:27], off offset:2048 sc1
	s_nop 1
	v_sub_f32_e32 v24, v28, v131
	v_sub_f32_e32 v28, v32, v135
	s_waitcnt vmcnt(15)
	v_lshlrev_b32_e32 v32, 16, v20
	v_add_f32_e32 v36, v24, v32
	v_min_u32_e32 v24, 5, v129
	v_add_u32_e32 v24, 11, v24
	v_sub_f32_e32 v25, v29, v132
	v_and_b32_e32 v20, 0xffff0000, v20
	v_cvt_f32_ubyte0_e32 v24, v24
	v_sub_f32_e32 v26, v30, v133
	v_sub_f32_e32 v29, v33, v136
	v_lshlrev_b32_e32 v33, 16, v21
	v_add_f32_e32 v37, v25, v20
	v_div_scale_f32 v25, s[8:9], v24, v24, 1.0
	v_add_f32_e32 v38, v26, v33
	v_rcp_f32_e32 v26, v25
	v_sub_f32_e32 v27, v31, v134
	v_and_b32_e32 v21, 0xffff0000, v21
	v_add_f32_e32 v39, v27, v21
	v_fma_f32 v27, -v25, v26, 1.0
	v_fmac_f32_e32 v26, v27, v26
	v_div_scale_f32 v27, vcc, 1.0, v24, 1.0
	v_mul_f32_e32 v40, v27, v26
	v_fma_f32 v41, -v25, v40, v27
	v_fmac_f32_e32 v40, v41, v26
	v_fma_f32 v25, -v25, v40, v27
	v_div_fmas_f32 v25, v25, v26, v40
	v_div_fixup_f32 v24, v25, v24, 1.0
	v_sub_f32_e32 v30, v34, v137
	v_lshlrev_b32_e32 v34, 16, v22
	v_and_b32_e32 v22, 0xffff0000, v22
	v_fma_f32 v25, v24, v36, -v32
	v_fma_f32 v20, v24, v37, -v20
	v_sub_f32_e32 v31, v35, v138
	v_lshlrev_b32_e32 v35, 16, v23
	v_and_b32_e32 v23, 0xffff0000, v23
	v_add_f32_e32 v28, v28, v34
	v_add_f32_e32 v29, v29, v22
	v_cvt_pk_bf16_f32 v20, v25, v20
	v_fma_f32 v25, v24, v38, -v33
	v_fma_f32 v21, v24, v39, -v21
	v_add_f32_e32 v30, v30, v35
	v_add_f32_e32 v31, v31, v23
	v_cvt_pk_bf16_f32 v21, v25, v21
	v_fma_f32 v25, v24, v28, -v34
	v_fma_f32 v22, v24, v29, -v22
	v_cvt_pk_bf16_f32 v22, v25, v22
	v_fma_f32 v25, v24, v30, -v35
	v_fma_f32 v23, v24, v31, -v23
	v_add_co_u32_e32 v24, vcc, s5, v124
	v_cvt_pk_bf16_f32 v23, v25, v23
	s_waitcnt vmcnt(14)
; __device__ __forceinline__ unsigned cvt_pk_bf16(float lo, float hi) { unsigned r; asm volatile("v_cvt_pk_bf16_f32 %0, %1, %2" : "=v"(r) : "v"(lo), "v"(hi)); return r; }
; #define UNPK8(q, f) const float f[8] = {bf_lo((q).x), bf_hi((q).x), bf_lo((q).y), bf_hi((q).y), bf_lo((q).z), bf_hi((q).z), bf_lo((q).w), bf_hi((q).w)}
; template <int W> __device__ __forceinline__ void pool_run(const bf16_t* up, bf16_t* dp, int t0) {
;     ...
;     for (int j = 0; j < 16; ++j) {
;         UNPK8(q[j + W - 1], cur);
; #pragma unroll
;         for (int e = 0; e < 8; ++e) s[e] += cur[e];
;         const int cnt = (t0 + j + 1) < W ? (t0 + j + 1) : W; const float inv = 1.0f / (float)cnt;
;         u32x4 o; o.x = cvt_pk_bf16(s[0] * inv - cur[0], s[1] * inv - cur[1]); o.y = cvt_pk_bf16(s[2] * inv - cur[2], s[3] * inv - cur[3]);
;         o.z = cvt_pk_bf16(s[4] * inv - cur[4], s[5] * inv - cur[5]); o.w = cvt_pk_bf16(s[6] * inv - cur[6], s[7] * inv - cur[7]);
;         *(u32x4*)(dp + (size_t)j * PW) = o;
;         UNPK8(q[j], old);
; #pragma unroll
;         for (int e = 0; e < 8; ++e) s[e] -= old[e];
;     }
	v_lshlrev_b32_e32 v32, 16, v16
	v_addc_co_u32_e32 v25, vcc, 0, v125, vcc
	v_add_co_u32_e32 v26, vcc, s6, v124
	v_and_b32_e32 v16, 0xffff0000, v16
	s_nop 0
	v_addc_co_u32_e32 v27, vcc, 0, v125, vcc
	global_store_dwordx4 v[26:27], v[20:23], off offset:-4096 sc1
	v_sub_f32_e32 v29, v29, v93
	v_lshlrev_b32_e32 v33, 16, v17
	v_sub_f32_e32 v20, v36, v88
	v_min_u32_e32 v36, 4, v129
	v_add_u32_e32 v36, 12, v36
	v_cvt_f32_ubyte0_e32 v36, v36
	v_sub_f32_e32 v21, v37, v89
	v_div_scale_f32 v37, s[6:7], v36, v36, 1.0
	v_sub_f32_e32 v22, v38, v90
	v_rcp_f32_e32 v38, v37
	v_sub_f32_e32 v23, v39, v91
	v_and_b32_e32 v17, 0xffff0000, v17
	v_lshlrev_b32_e32 v34, 16, v18
	v_fma_f32 v39, -v37, v38, 1.0
	v_fmac_f32_e32 v38, v39, v38
	v_div_scale_f32 v39, vcc, 1.0, v36, 1.0
	v_mul_f32_e32 v40, v39, v38
	v_fma_f32 v41, -v37, v40, v39
	v_fmac_f32_e32 v40, v41, v38
	v_fma_f32 v37, -v37, v40, v39
	v_div_fmas_f32 v37, v37, v38, v40
	v_and_b32_e32 v18, 0xffff0000, v18
	v_add_f32_e32 v20, v20, v32
	v_add_f32_e32 v21, v21, v16
	v_div_fixup_f32 v36, v37, v36, 1.0
	v_sub_f32_e32 v28, v28, v92
	v_sub_f32_e32 v31, v31, v95
	v_lshlrev_b32_e32 v35, 16, v19
	v_and_b32_e32 v19, 0xffff0000, v19
	v_add_f32_e32 v22, v22, v33
	v_add_f32_e32 v23, v23, v17
	v_add_f32_e32 v29, v29, v18
	v_fma_f32 v32, v36, v20, -v32
	v_fma_f32 v16, v36, v21, -v16
	v_sub_f32_e32 v30, v30, v94
	v_add_f32_e32 v28, v28, v34
	v_add_f32_e32 v31, v31, v19
	v_cvt_pk_bf16_f32 v16, v32, v16
	v_fma_f32 v32, v36, v22, -v33
	v_fma_f32 v17, v36, v23, -v17
	v_fma_f32 v18, v36, v29, -v18
	v_add_f32_e32 v30, v30, v35
	v_cvt_pk_bf16_f32 v17, v32, v17
	v_fma_f32 v32, v36, v28, -v34
	v_cvt_pk_bf16_f32 v18, v32, v18
	v_fma_f32 v19, v36, v31, -v19
	v_fma_f32 v32, v36, v30, -v35
	v_cvt_pk_bf16_f32 v19, v32, v19
	global_store_dwordx4 v[24:25], v[16:19], off offset:2048 sc1
	s_waitcnt vmcnt(15)
	v_lshlrev_b32_e32 v24, 16, v12
	v_and_b32_e32 v12, 0xffff0000, v12
	v_sub_f32_e32 v18, v22, v78
	v_sub_f32_e32 v22, v30, v82
	v_min_u32_e32 v30, 3, v129
	v_add_u32_e32 v30, 13, v30
	v_cvt_f32_ubyte0_e32 v30, v30
	v_sub_f32_e32 v19, v23, v79
	v_sub_f32_e32 v23, v31, v83
	v_div_scale_f32 v31, s[6:7], v30, v30, 1.0
	v_rcp_f32_e32 v32, v31
	v_sub_f32_e32 v16, v20, v76
	v_sub_f32_e32 v17, v21, v77
	v_lshlrev_b32_e32 v25, 16, v13
	v_fma_f32 v33, -v31, v32, 1.0
	v_fmac_f32_e32 v32, v33, v32
	v_div_scale_f32 v33, vcc, 1.0, v30, 1.0
	v_mul_f32_e32 v34, v33, v32
	v_fma_f32 v35, -v31, v34, v33
	v_fmac_f32_e32 v34, v35, v32
	v_fma_f32 v31, -v31, v34, v33
	v_div_fmas_f32 v31, v31, v32, v34
	v_and_b32_e32 v13, 0xffff0000, v13
	v_add_f32_e32 v16, v16, v24
	v_add_f32_e32 v17, v17, v12
	v_div_fixup_f32 v30, v31, v30, 1.0
	v_sub_f32_e32 v20, v28, v80
	v_sub_f32_e32 v21, v29, v81
	v_lshlrev_b32_e32 v28, 16, v14
	v_and_b32_e32 v14, 0xffff0000, v14
	v_add_f32_e32 v18, v18, v25
	v_add_f32_e32 v19, v19, v13
	v_fma_f32 v24, v30, v16, -v24
	v_fma_f32 v12, v30, v17, -v12
	v_lshlrev_b32_e32 v29, 16, v15
	v_and_b32_e32 v15, 0xffff0000, v15
	v_add_f32_e32 v20, v20, v28
	v_add_f32_e32 v21, v21, v14
	v_cvt_pk_bf16_f32 v12, v24, v12
	v_fma_f32 v24, v30, v18, -v25
	v_fma_f32 v13, v30, v19, -v13
	v_add_f32_e32 v22, v22, v29
	v_add_f32_e32 v23, v23, v15
	v_cvt_pk_bf16_f32 v13, v24, v13
	v_fma_f32 v24, v30, v20, -v28
	v_fma_f32 v14, v30, v21, -v14
	v_cvt_pk_bf16_f32 v14, v24, v14
	v_fma_f32 v24, v30, v22, -v29
	v_fma_f32 v15, v30, v23, -v15
	v_cvt_pk_bf16_f32 v15, v24, v15
	v_min_u32_e32 v24, 2, v129
	v_add_u32_e32 v24, 14, v24
	v_cvt_f32_ubyte0_e32 v24, v24
	v_div_scale_f32 v25, s[6:7], v24, v24, 1.0
	v_rcp_f32_e32 v28, v25
	global_store_dwordx4 v[26:27], v[12:15], off sc1
	v_fma_f32 v29, -v25, v28, 1.0
	v_fmac_f32_e32 v28, v29, v28
	v_div_scale_f32 v29, vcc, 1.0, v24, 1.0
	v_mul_f32_e32 v30, v29, v28
	v_fma_f32 v31, -v25, v30, v29
	v_fmac_f32_e32 v30, v31, v28
	v_fma_f32 v25, -v25, v30, v29
	v_sub_f32_e32 v12, v16, v68
	v_sub_f32_e32 v13, v17, v69
	v_sub_f32_e32 v16, v20, v72
	s_waitcnt vmcnt(15)
; __device__ __forceinline__ unsigned cvt_pk_bf16(float lo, float hi) { unsigned r; asm volatile("v_cvt_pk_bf16_f32 %0, %1, %2" : "=v"(r) : "v"(lo), "v"(hi)); return r; }
; #define UNPK8(q, f) const float f[8] = {bf_lo((q).x), bf_hi((q).x), bf_lo((q).y), bf_hi((q).y), bf_lo((q).z), bf_hi((q).z), bf_lo((q).w), bf_hi((q).w)}
; template <int W> __device__ __forceinline__ void pool_run(const bf16_t* up, bf16_t* dp, int t0) {
;     ...
;     for (int j = 0; j < 16; ++j) {
;         UNPK8(q[j + W - 1], cur);
; #pragma unroll
;         for (int e = 0; e < 8; ++e) s[e] += cur[e];
;         const int cnt = (t0 + j + 1) < W ? (t0 + j + 1) : W; const float inv = 1.0f / (float)cnt;
;         u32x4 o; o.x = cvt_pk_bf16(s[0] * inv - cur[0], s[1] * inv - cur[1]); o.y = cvt_pk_bf16(s[2] * inv - cur[2], s[3] * inv - cur[3]);
;         o.z = cvt_pk_bf16(s[4] * inv - cur[4], s[5] * inv - cur[5]); o.w = cvt_pk_bf16(s[6] * inv - cur[6], s[7] * inv - cur[7]);
;         *(u32x4*)(dp + (size_t)j * PW) = o;
;         UNPK8(q[j], old);
; #pragma unroll
;         for (int e = 0; e < 8; ++e) s[e] -= old[e];
;     }
	v_lshlrev_b32_e32 v20, 16, v8
	v_and_b32_e32 v8, 0xffff0000, v8
	v_div_fmas_f32 v25, v25, v28, v30
	v_sub_f32_e32 v14, v18, v70
	v_sub_f32_e32 v15, v19, v71
	v_sub_f32_e32 v17, v21, v73
	v_lshlrev_b32_e32 v21, 16, v9
	v_and_b32_e32 v9, 0xffff0000, v9
	v_add_f32_e32 v12, v12, v20
	v_add_f32_e32 v13, v13, v8
	v_div_fixup_f32 v24, v25, v24, 1.0
	v_sub_f32_e32 v18, v22, v74
	v_sub_f32_e32 v19, v23, v75
	v_lshlrev_b32_e32 v22, 16, v10
	v_and_b32_e32 v10, 0xffff0000, v10
	v_lshlrev_b32_e32 v23, 16, v11
	v_and_b32_e32 v11, 0xffff0000, v11
	v_add_f32_e32 v14, v14, v21
	v_add_f32_e32 v15, v15, v9
	v_fma_f32 v20, v24, v12, -v20
	v_fma_f32 v8, v24, v13, -v8
	v_add_f32_e32 v16, v16, v22
	v_add_f32_e32 v17, v17, v10
	v_add_f32_e32 v19, v19, v11
	v_cvt_pk_bf16_f32 v8, v20, v8
	v_fma_f32 v20, v24, v14, -v21
	v_fma_f32 v9, v24, v15, -v9
	v_add_f32_e32 v18, v18, v23
	v_cvt_pk_bf16_f32 v9, v20, v9
	v_fma_f32 v20, v24, v16, -v22
	v_fma_f32 v10, v24, v17, -v10
	v_fma_f32 v11, v24, v19, -v11
	v_cvt_pk_bf16_f32 v10, v20, v10
	v_fma_f32 v20, v24, v18, -v23
	v_cvt_pk_bf16_f32 v11, v20, v11
	global_store_dwordx4 v[26:27], v[8:11], off offset:2048 sc1
	s_nop 1
	v_sub_f32_e32 v8, v12, v56
	v_sub_f32_e32 v12, v16, v60
	s_waitcnt vmcnt(15)
	v_lshlrev_b32_e32 v16, 16, v4
	v_sub_f32_e32 v9, v13, v57
	v_and_b32_e32 v4, 0xffff0000, v4
	v_add_f32_e32 v20, v8, v16
	v_div_scale_f32 v8, s[6:7], v130, v130, 1.0
	v_add_f32_e32 v21, v9, v4
	v_rcp_f32_e32 v9, v8
	v_sub_f32_e32 v10, v14, v58
	v_sub_f32_e32 v11, v15, v59
	v_sub_f32_e32 v13, v17, v61
	v_fma_f32 v22, -v8, v9, 1.0
	v_fmac_f32_e32 v9, v22, v9
	v_div_scale_f32 v22, vcc, 1.0, v130, 1.0
	v_mul_f32_e32 v23, v22, v9
	v_fma_f32 v24, -v8, v23, v22
	v_fmac_f32_e32 v23, v24, v9
	v_fma_f32 v8, -v8, v23, v22
	v_div_fmas_f32 v8, v8, v9, v23
	v_lshlrev_b32_e32 v17, 16, v5
	v_and_b32_e32 v5, 0xffff0000, v5
	v_div_fixup_f32 v8, v8, v130, 1.0
	v_sub_f32_e32 v14, v18, v62
	v_lshlrev_b32_e32 v18, 16, v6
	v_and_b32_e32 v6, 0xffff0000, v6
	v_add_f32_e32 v10, v10, v17
	v_add_f32_e32 v11, v11, v5
	v_fma_f32 v9, v8, v20, -v16
	v_fma_f32 v4, v8, v21, -v4
	v_sub_f32_e32 v15, v19, v63
	v_lshlrev_b32_e32 v19, 16, v7
	v_and_b32_e32 v7, 0xffff0000, v7
	v_add_f32_e32 v12, v12, v18
	v_add_f32_e32 v13, v13, v6
	v_cvt_pk_bf16_f32 v4, v9, v4
	v_fma_f32 v9, v8, v10, -v17
	v_fma_f32 v5, v8, v11, -v5
	v_add_f32_e32 v14, v14, v19
	v_add_f32_e32 v15, v15, v7
	v_cvt_pk_bf16_f32 v5, v9, v5
	v_fma_f32 v9, v8, v12, -v18
	v_fma_f32 v6, v8, v13, -v6
	v_cvt_pk_bf16_f32 v6, v9, v6
	v_fma_f32 v9, v8, v14, -v19
	v_fma_f32 v7, v8, v15, -v7
	v_add_co_u32_e32 v8, vcc, s4, v124
	v_cvt_pk_bf16_f32 v7, v9, v7
	s_mov_b32 s4, 0x3d800000
	s_nop 0
	v_addc_co_u32_e32 v9, vcc, 0, v125, vcc
	global_store_dwordx4 v[8:9], v[4:7], off sc1
	v_sub_f32_e32 v8, v12, v52
	s_waitcnt vmcnt(15)
	v_lshlrev_b32_e32 v12, 16, v0
	v_sub_f32_e32 v4, v20, v44
	v_sub_f32_e32 v5, v21, v45
	v_and_b32_e32 v0, 0xffff0000, v0
	v_sub_f32_e32 v6, v10, v46
	v_sub_f32_e32 v7, v11, v47
	v_sub_f32_e32 v9, v13, v53
	v_lshlrev_b32_e32 v13, 16, v1
	v_and_b32_e32 v1, 0xffff0000, v1
	v_add_f32_e32 v4, v4, v12
	v_add_f32_e32 v5, v5, v0
	v_sub_f32_e32 v10, v14, v54
	v_lshlrev_b32_e32 v14, 16, v2
	v_and_b32_e32 v2, 0xffff0000, v2
	v_add_f32_e32 v6, v6, v13
	v_add_f32_e32 v7, v7, v1
	v_fma_f32 v4, v4, s4, -v12
	v_fma_f32 v0, v5, s4, -v0
	v_sub_f32_e32 v11, v15, v55
	v_lshlrev_b32_e32 v15, 16, v3
	v_and_b32_e32 v3, 0xffff0000, v3
	v_add_f32_e32 v8, v8, v14
	v_add_f32_e32 v9, v9, v2
	v_cvt_pk_bf16_f32 v0, v4, v0
	v_fma_f32 v4, v6, s4, -v13
	v_fma_f32 v1, v7, s4, -v1
	v_add_f32_e32 v10, v10, v15
	v_add_f32_e32 v11, v11, v3
	v_cvt_pk_bf16_f32 v1, v4, v1
	v_fma_f32 v4, v8, s4, -v14
	v_fma_f32 v2, v9, s4, -v2
	v_cvt_pk_bf16_f32 v2, v4, v2
	v_fma_f32 v4, v10, s4, -v15
	v_fma_f32 v3, v11, s4, -v3
	v_cvt_pk_bf16_f32 v3, v4, v3
